# single early buffer_wbl2 per XCD at 87.5 percent arrival
# baseline (speedup 1.0000x reference)
; __device__ __forceinline__ unsigned xb_ld(unsigned* p)              { return __hip_atomic_load(p, __ATOMIC_RELAXED, __HIP_MEMORY_SCOPE_AGENT); }
; __device__ __forceinline__ unsigned xb_add(unsigned* p, unsigned v) { return __hip_atomic_fetch_add(p, v, __ATOMIC_RELAXED, __HIP_MEMORY_SCOPE_AGENT); }
; #define XB_SPIN(cond, bar) do { unsigned _sp = 0; while (cond) { __builtin_amdgcn_s_sleep(0); \
;     if ((++_sp & 255u) == 0u) { if (xb_ld(&(bar)[XB_TMO])) break; if (_sp > XB_SPIN_CAP) { atomicAdd(&(bar)[XB_TMO], 1u); break; } } } } while (0)
; __device__ __forceinline__ void xcd_barrier(const XcdBarrier& b) {
;     ...
;         const unsigned old = xb_add(&bar[XB_XSUB(b.x)], 1u);
;         const unsigned gen = old / nloc;
;         if (old + 1u == (gen + 1u) * nloc) {
;             __builtin_amdgcn_fence(__ATOMIC_RELEASE, "agent");
;     ...
;             XB_SPIN(xb_ld(&bar[XB_XGEN(b.x)]) == gen, bar);
.LBB0_155:
	s_or_b64 exec, exec, s[0:1]
	v_cvt_f32_u32_e32 v4, v2
	s_waitcnt vmcnt(0)
	v_readfirstlane_b32 s0, v3
	v_sub_u32_e32 v3, 0, v2
	v_rcp_iflag_f32_e32 v4, v4
	v_add_u32_e32 v5, s0, v1
	v_mul_f32_e32 v4, 0x4f7ffffe, v4
	v_cvt_u32_f32_e32 v4, v4
	v_mul_lo_u32 v1, v3, v4
	v_mul_hi_u32 v1, v4, v1
	v_add_u32_e32 v1, v4, v1
	v_mul_hi_u32 v1, v5, v1
	v_mul_lo_u32 v3, v1, v2
	v_sub_u32_e32 v3, v5, v3
	v_add_u32_e32 v4, 1, v1
	v_cmp_ge_u32_e32 vcc, v3, v2
	s_nop 1
	v_cndmask_b32_e32 v1, v1, v4, vcc
	v_sub_u32_e32 v4, v3, v2
	v_cndmask_b32_e32 v3, v3, v4, vcc
	v_add_u32_e32 v4, 1, v1
	v_cmp_ge_u32_e32 vcc, v3, v2
	v_add_u32_e32 v3, 1, v5
	s_nop 0
	v_cndmask_b32_e32 v1, v1, v4, vcc
	v_mul_lo_u32 v4, v2, v1
	v_add_u32_e32 v2, v4, v2
	v_cmp_ne_u32_e32 vcc, v3, v2
	s_and_saveexec_b64 s[0:1], vcc
	s_xor_b64 s[0:1], exec, s[0:1]
	s_cbranch_execz .LBB0_169
	v_readlane_b32 s2, v252, 7
	v_readlane_b32 s3, v252, 8
	s_waitcnt lgkmcnt(0)
	v_mad_u32_u24 v1, v0, v1, v0
	v_sub_u32_e32 v3, v3, v4
	v_sub_u32_e32 v4, v2, v4
	v_lshlrev_b32_e32 v3, 3, v3
	v_mul_u32_u24_e32 v4, 7, v4
	v_cmp_eq_u32_e32 vcc, v3, v4
	s_cbranch_vccz .Lewb_skip0
	buffer_wbl2 sc1
